# nt hint also on the once-read bf16 row inputs (x16, Y, split-K partials) of the two residual/norm row phases
# baseline (speedup 1.0000x reference)
.LBB0_270:
	v_readlane_b32 s4, v255, 6
	s_movk_i32 s0, 0x1fff
	v_mov_b32_e32 v46, v88
	v_readlane_b32 s5, v255, 7
	v_cmp_gt_i32_e64 s[36:37], s33, v44
	v_cmp_lt_i32_e64 s[0:1], s0, v44
	s_mov_b64 s[2:3], -1
	v_ashrrev_i32_e32 v47, 31, v46
	s_and_b64 vcc, exec, s[4:5]
	v_ashrrev_i32_e32 v45, 31, v44
	s_cbranch_vccz .LBB0_272
	v_readlane_b32 s2, v252, 26
	v_lshlrev_b64 v[0:1], 12, v[44:45]
	v_readlane_b32 s3, v252, 27
	s_nop 1
	v_lshl_add_u64 v[0:1], s[2:3], 0, v[0:1]
	v_lshl_add_u64 v[0:1], v[46:47], 1, v[0:1]
	global_load_dwordx2 v[2:3], v[0:1], off nt
	global_load_dwordx2 v[4:5], v[0:1], off offset:512 nt
	global_load_dwordx2 v[6:7], v[0:1], off offset:1024 nt
	global_load_dwordx2 v[10:11], v[0:1], off offset:1536 nt
	global_load_dwordx2 v[12:13], v[0:1], off offset:2048 nt
	global_load_dwordx2 v[14:15], v[0:1], off offset:2560 nt
	global_load_dwordx2 v[32:33], v[0:1], off offset:3072 nt
	global_load_dwordx2 v[34:35], v[0:1], off offset:3584 nt
	s_waitcnt vmcnt(0)
	v_lshlrev_b32_e32 v28, 16, v2
	v_and_b32_e32 v29, 0xffff0000, v2
	v_lshlrev_b32_e32 v30, 16, v3
	v_and_b32_e32 v31, 0xffff0000, v3
	v_lshlrev_b32_e32 v24, 16, v4
	v_and_b32_e32 v25, 0xffff0000, v4
	v_lshlrev_b32_e32 v26, 16, v5
	v_and_b32_e32 v27, 0xffff0000, v5
	v_lshlrev_b32_e32 v16, 16, v6
	v_and_b32_e32 v17, 0xffff0000, v6
	v_lshlrev_b32_e32 v18, 16, v7
	v_and_b32_e32 v19, 0xffff0000, v7
	v_lshlrev_b32_e32 v8, 16, v10
	v_and_b32_e32 v9, 0xffff0000, v10
	v_lshlrev_b32_e32 v10, 16, v11
	v_and_b32_e32 v11, 0xffff0000, v11
	v_lshlrev_b32_e32 v20, 16, v12
	v_and_b32_e32 v21, 0xffff0000, v12
	v_lshlrev_b32_e32 v22, 16, v13
	v_and_b32_e32 v23, 0xffff0000, v13
	v_lshlrev_b32_e32 v12, 16, v14
	v_and_b32_e32 v13, 0xffff0000, v14
	v_lshlrev_b32_e32 v14, 16, v15
	v_and_b32_e32 v15, 0xffff0000, v15
	v_lshlrev_b32_e32 v4, 16, v32
	v_and_b32_e32 v5, 0xffff0000, v32
	v_lshlrev_b32_e32 v6, 16, v33
	v_and_b32_e32 v7, 0xffff0000, v33
	v_lshlrev_b32_e32 v0, 16, v34
	v_and_b32_e32 v1, 0xffff0000, v34
	v_lshlrev_b32_e32 v2, 16, v35
	v_and_b32_e32 v3, 0xffff0000, v35
	v_add_u32_e32 v192, 0xffffe000, v44
	s_cbranch_execnz .LBB0_274
	s_branch .LBB0_273

.LBB0_276:
	v_lshl_add_u64 v[34:35], s[2:3], 1, v[32:33]
	global_load_dwordx2 v[36:37], v[34:35], off nt
	global_load_dwordx2 v[38:39], v[34:35], off offset:512 nt
	global_load_dwordx2 v[40:41], v[34:35], off offset:1024 nt
	global_load_dwordx2 v[42:43], v[34:35], off offset:1536 nt
	global_load_dwordx2 v[80:81], v[34:35], off offset:2048 nt
	global_load_dwordx2 v[82:83], v[34:35], off offset:2560 nt
	global_load_dwordx2 v[84:85], v[34:35], off offset:3072 nt
	global_load_dwordx2 v[86:87], v[34:35], off offset:3584 nt
	v_add_co_u32_e32 v90, vcc, s42, v34
	s_mov_b64 s[2:3], 0x800000
	s_nop 0
	v_addc_co_u32_e32 v91, vcc, 0, v35, vcc
	global_load_dwordx2 v[92:93], v[90:91], off nt
	global_load_dwordx2 v[94:95], v[90:91], off offset:512 nt
	global_load_dwordx2 v[96:97], v[90:91], off offset:1024 nt
	global_load_dwordx2 v[98:99], v[90:91], off offset:1536 nt
	global_load_dwordx2 v[100:101], v[90:91], off offset:2048 nt
	global_load_dwordx2 v[102:103], v[90:91], off offset:2560 nt
	global_load_dwordx2 v[104:105], v[90:91], off offset:3072 nt
	s_nop 0
	global_load_dwordx2 v[90:91], v[90:91], off offset:3584 nt
	v_add_co_u32_e32 v106, vcc, s96, v34
	s_waitcnt vmcnt(0)
	v_lshlrev_b32_e32 v136, 16, v36
	v_addc_co_u32_e32 v107, vcc, 0, v35, vcc
	global_load_dwordx2 v[108:109], v[106:107], off nt
	global_load_dwordx2 v[110:111], v[106:107], off offset:512 nt
	global_load_dwordx2 v[112:113], v[106:107], off offset:1024 nt
	global_load_dwordx2 v[114:115], v[106:107], off offset:1536 nt
	global_load_dwordx2 v[116:117], v[106:107], off offset:2048 nt
	global_load_dwordx2 v[118:119], v[106:107], off offset:2560 nt
	global_load_dwordx2 v[120:121], v[106:107], off offset:3072 nt
	s_nop 0
	global_load_dwordx2 v[106:107], v[106:107], off offset:3584 nt
	v_add_co_u32_e32 v34, vcc, s43, v34
	v_and_b32_e32 v137, 0xffff0000, v36
	s_nop 0
	v_addc_co_u32_e32 v35, vcc, 0, v35, vcc
	global_load_dwordx2 v[122:123], v[34:35], off nt
	global_load_dwordx2 v[124:125], v[34:35], off offset:512 nt
	global_load_dwordx2 v[126:127], v[34:35], off offset:1024 nt
	global_load_dwordx2 v[128:129], v[34:35], off offset:1536 nt
	global_load_dwordx2 v[130:131], v[34:35], off offset:2048 nt
	global_load_dwordx2 v[132:133], v[34:35], off offset:2560 nt
	global_load_dwordx2 v[134:135], v[34:35], off offset:3072 nt
	s_nop 0
	global_load_dwordx2 v[34:35], v[34:35], off offset:3584 nt
	v_lshlrev_b32_e32 v36, 16, v37
	v_and_b32_e32 v37, 0xffff0000, v37
	v_pk_add_f32 v[36:37], v[50:51], v[36:37]
	v_lshlrev_b32_e32 v50, 16, v38
	v_and_b32_e32 v51, 0xffff0000, v38
	v_pk_add_f32 v[50:51], v[52:53], v[50:51]
	v_lshlrev_b32_e32 v52, 16, v40
	v_and_b32_e32 v53, 0xffff0000, v40
	v_lshlrev_b32_e32 v40, 16, v41
	v_and_b32_e32 v41, 0xffff0000, v41
	v_pk_add_f32 v[52:53], v[56:57], v[52:53]
	v_lshlrev_b32_e32 v56, 16, v80
	v_and_b32_e32 v57, 0xffff0000, v80
	v_pk_add_f32 v[40:41], v[58:59], v[40:41]
	v_lshlrev_b32_e32 v58, 16, v81
	v_and_b32_e32 v59, 0xffff0000, v81
	v_pk_add_f32 v[56:57], v[64:65], v[56:57]
	v_lshlrev_b32_e32 v64, 16, v84
	v_and_b32_e32 v65, 0xffff0000, v84
	v_pk_add_f32 v[48:49], v[48:49], v[136:137]
	v_pk_add_f32 v[58:59], v[66:67], v[58:59]
	v_lshlrev_b32_e32 v66, 16, v85
	v_and_b32_e32 v67, 0xffff0000, v85
	v_pk_add_f32 v[64:65], v[72:73], v[64:65]
	v_lshlrev_b32_e32 v72, 16, v92
	v_and_b32_e32 v73, 0xffff0000, v92
	v_lshlrev_b32_e32 v38, 16, v39
	v_and_b32_e32 v39, 0xffff0000, v39
	v_pk_add_f32 v[66:67], v[74:75], v[66:67]
	v_lshlrev_b32_e32 v74, 16, v93
	v_and_b32_e32 v75, 0xffff0000, v93
	v_pk_add_f32 v[48:49], v[48:49], v[72:73]
	v_lshlrev_b32_e32 v72, 16, v94
	v_and_b32_e32 v73, 0xffff0000, v94
	v_pk_add_f32 v[38:39], v[54:55], v[38:39]
	v_lshlrev_b32_e32 v54, 16, v42
	v_and_b32_e32 v55, 0xffff0000, v42
	v_pk_add_f32 v[36:37], v[36:37], v[74:75]
	v_lshlrev_b32_e32 v74, 16, v95
	v_and_b32_e32 v75, 0xffff0000, v95
	v_pk_add_f32 v[50:51], v[50:51], v[72:73]
	v_lshlrev_b32_e32 v72, 16, v96
	v_and_b32_e32 v73, 0xffff0000, v96
	v_lshlrev_b32_e32 v42, 16, v43
	v_and_b32_e32 v43, 0xffff0000, v43
	v_pk_add_f32 v[54:55], v[60:61], v[54:55]
	v_pk_add_f32 v[38:39], v[38:39], v[74:75]
	v_lshlrev_b32_e32 v74, 16, v97
	v_and_b32_e32 v75, 0xffff0000, v97
	v_pk_add_f32 v[52:53], v[52:53], v[72:73]
	v_lshlrev_b32_e32 v72, 16, v98
	v_and_b32_e32 v73, 0xffff0000, v98
	v_pk_add_f32 v[42:43], v[62:63], v[42:43]
	v_lshlrev_b32_e32 v60, 16, v82
	v_and_b32_e32 v61, 0xffff0000, v82
	v_pk_add_f32 v[40:41], v[40:41], v[74:75]
	v_lshlrev_b32_e32 v74, 16, v99
	v_and_b32_e32 v75, 0xffff0000, v99
	v_pk_add_f32 v[54:55], v[54:55], v[72:73]
	v_lshlrev_b32_e32 v72, 16, v100
	v_and_b32_e32 v73, 0xffff0000, v100
	v_lshlrev_b32_e32 v62, 16, v83
	v_and_b32_e32 v63, 0xffff0000, v83
	v_pk_add_f32 v[60:61], v[68:69], v[60:61]
	v_pk_add_f32 v[42:43], v[42:43], v[74:75]
	v_lshlrev_b32_e32 v74, 16, v101
	v_and_b32_e32 v75, 0xffff0000, v101
	v_pk_add_f32 v[56:57], v[56:57], v[72:73]
	v_lshlrev_b32_e32 v72, 16, v102
	v_and_b32_e32 v73, 0xffff0000, v102
	v_pk_add_f32 v[62:63], v[70:71], v[62:63]
	v_lshlrev_b32_e32 v68, 16, v86
	v_and_b32_e32 v69, 0xffff0000, v86
	v_pk_add_f32 v[58:59], v[58:59], v[74:75]
	v_lshlrev_b32_e32 v74, 16, v103
	v_and_b32_e32 v75, 0xffff0000, v103
	v_pk_add_f32 v[60:61], v[60:61], v[72:73]
	v_lshlrev_b32_e32 v72, 16, v104
	v_and_b32_e32 v73, 0xffff0000, v104
	v_lshlrev_b32_e32 v70, 16, v87
	v_and_b32_e32 v71, 0xffff0000, v87
	v_pk_add_f32 v[68:69], v[76:77], v[68:69]
	v_pk_add_f32 v[62:63], v[62:63], v[74:75]
	v_lshlrev_b32_e32 v74, 16, v105
	v_and_b32_e32 v75, 0xffff0000, v105
	v_pk_add_f32 v[64:65], v[64:65], v[72:73]
	v_lshlrev_b32_e32 v72, 16, v90
	v_and_b32_e32 v73, 0xffff0000, v90
	v_pk_add_f32 v[70:71], v[78:79], v[70:71]
	v_pk_add_f32 v[66:67], v[66:67], v[74:75]
	v_lshlrev_b32_e32 v74, 16, v91
	v_and_b32_e32 v75, 0xffff0000, v91
	v_pk_add_f32 v[68:69], v[68:69], v[72:73]
	s_waitcnt vmcnt(0)
	v_lshlrev_b32_e32 v72, 16, v108
	v_and_b32_e32 v73, 0xffff0000, v108
	v_pk_add_f32 v[70:71], v[70:71], v[74:75]
	v_lshlrev_b32_e32 v74, 16, v109
	v_and_b32_e32 v75, 0xffff0000, v109
	v_pk_add_f32 v[48:49], v[48:49], v[72:73]
	v_lshlrev_b32_e32 v72, 16, v110
	v_and_b32_e32 v73, 0xffff0000, v110
	v_pk_add_f32 v[36:37], v[36:37], v[74:75]
	v_lshlrev_b32_e32 v74, 16, v111
	v_and_b32_e32 v75, 0xffff0000, v111
	v_pk_add_f32 v[72:73], v[50:51], v[72:73]
	v_lshlrev_b32_e32 v50, 16, v112
	v_and_b32_e32 v51, 0xffff0000, v112
	v_pk_add_f32 v[38:39], v[38:39], v[74:75]
	v_lshlrev_b32_e32 v74, 16, v113
	v_and_b32_e32 v75, 0xffff0000, v113
	v_pk_add_f32 v[76:77], v[52:53], v[50:51]
	v_lshlrev_b32_e32 v50, 16, v114
	v_and_b32_e32 v51, 0xffff0000, v114
	v_lshlrev_b32_e32 v52, 16, v115
	v_and_b32_e32 v53, 0xffff0000, v115
	v_pk_add_f32 v[40:41], v[40:41], v[74:75]
	v_pk_add_f32 v[74:75], v[54:55], v[50:51]
	v_pk_add_f32 v[42:43], v[42:43], v[52:53]
	v_lshlrev_b32_e32 v50, 16, v116
	v_and_b32_e32 v51, 0xffff0000, v116
	v_lshlrev_b32_e32 v52, 16, v117
	v_and_b32_e32 v53, 0xffff0000, v117
	v_pk_add_f32 v[78:79], v[56:57], v[50:51]
	v_pk_add_f32 v[80:81], v[58:59], v[52:53]
	v_lshlrev_b32_e32 v50, 16, v118
	v_and_b32_e32 v51, 0xffff0000, v118
	v_lshlrev_b32_e32 v52, 16, v119
	v_and_b32_e32 v53, 0xffff0000, v119
	v_pk_add_f32 v[82:83], v[60:61], v[50:51]
	v_pk_add_f32 v[84:85], v[62:63], v[52:53]
	v_lshlrev_b32_e32 v50, 16, v120
	v_and_b32_e32 v51, 0xffff0000, v120
	v_lshlrev_b32_e32 v52, 16, v121
	v_and_b32_e32 v53, 0xffff0000, v121
	v_pk_add_f32 v[86:87], v[64:65], v[50:51]
	v_pk_add_f32 v[90:91], v[66:67], v[52:53]
	v_lshlrev_b32_e32 v50, 16, v106
	v_and_b32_e32 v51, 0xffff0000, v106
	v_lshlrev_b32_e32 v52, 16, v107
	v_and_b32_e32 v53, 0xffff0000, v107
	v_pk_add_f32 v[92:93], v[68:69], v[50:51]
	v_pk_add_f32 v[94:95], v[70:71], v[52:53]
	v_lshlrev_b32_e32 v52, 16, v122
	v_and_b32_e32 v53, 0xffff0000, v122
	v_lshlrev_b32_e32 v50, 16, v123
	v_and_b32_e32 v51, 0xffff0000, v123
	v_pk_add_f32 v[50:51], v[36:37], v[50:51]
	v_pk_add_f32 v[48:49], v[48:49], v[52:53]
	v_lshlrev_b32_e32 v36, 16, v124
	v_and_b32_e32 v37, 0xffff0000, v124
	v_lshlrev_b32_e32 v52, 16, v125
	v_and_b32_e32 v53, 0xffff0000, v125
	v_pk_add_f32 v[54:55], v[38:39], v[52:53]
	v_pk_add_f32 v[52:53], v[72:73], v[36:37]
	v_lshlrev_b32_e32 v36, 16, v126
	v_and_b32_e32 v37, 0xffff0000, v126
	v_lshlrev_b32_e32 v38, 16, v127
	v_and_b32_e32 v39, 0xffff0000, v127
	v_pk_add_f32 v[56:57], v[76:77], v[36:37]
	v_lshlrev_b32_e32 v36, 16, v128
	v_and_b32_e32 v37, 0xffff0000, v128
	v_pk_add_f32 v[58:59], v[40:41], v[38:39]
	v_lshlrev_b32_e32 v38, 16, v129
	v_and_b32_e32 v39, 0xffff0000, v129
	v_pk_add_f32 v[60:61], v[74:75], v[36:37]
	v_lshlrev_b32_e32 v36, 16, v130
	v_and_b32_e32 v37, 0xffff0000, v130
	v_pk_add_f32 v[62:63], v[42:43], v[38:39]
	v_lshlrev_b32_e32 v38, 16, v131
	v_and_b32_e32 v39, 0xffff0000, v131
	v_pk_add_f32 v[64:65], v[78:79], v[36:37]
	v_lshlrev_b32_e32 v36, 16, v132
	v_and_b32_e32 v37, 0xffff0000, v132
	v_pk_add_f32 v[66:67], v[80:81], v[38:39]
	v_lshlrev_b32_e32 v38, 16, v133
	v_and_b32_e32 v39, 0xffff0000, v133
	v_pk_add_f32 v[68:69], v[82:83], v[36:37]
	v_lshlrev_b32_e32 v36, 16, v134
	v_and_b32_e32 v37, 0xffff0000, v134
	v_pk_add_f32 v[70:71], v[84:85], v[38:39]
	v_lshlrev_b32_e32 v38, 16, v135
	v_and_b32_e32 v39, 0xffff0000, v135
	v_pk_add_f32 v[72:73], v[86:87], v[36:37]
	v_lshlrev_b32_e32 v36, 16, v34
	v_and_b32_e32 v37, 0xffff0000, v34
	v_lshlrev_b32_e32 v34, 16, v35
	v_and_b32_e32 v35, 0xffff0000, v35
	v_pk_add_f32 v[74:75], v[90:91], v[38:39]
	v_pk_add_f32 v[78:79], v[94:95], v[34:35]
	v_pk_add_f32 v[76:77], v[92:93], v[36:37]
	s_and_b64 vcc, exec, s[36:37]
	s_mov_b64 s[36:37], 0
	s_cbranch_vccnz .LBB0_276
	v_mov_b32_e32 v45, v193
	v_lshlrev_b64 v[80:81], 12, v[44:45]
	s_andn2_saveexec_b64 s[0:1], s[0:1]
	s_cbranch_execz .LBB0_269
	s_branch .LBB0_279

.LBB0_279:
	v_readlane_b32 s2, v252, 7
	v_lshlrev_b64 v[80:81], 12, v[44:45]
	v_readlane_b32 s3, v252, 8
	s_nop 1
	v_lshl_add_u64 v[32:33], s[2:3], 0, v[80:81]
	v_lshl_add_u64 v[32:33], v[46:47], 1, v[32:33]
	global_load_dwordx2 v[34:35], v[32:33], off nt
	global_load_dwordx2 v[36:37], v[32:33], off offset:512 nt
	global_load_dwordx2 v[38:39], v[32:33], off offset:1024 nt
	global_load_dwordx2 v[40:41], v[32:33], off offset:1536 nt
	global_load_dwordx2 v[42:43], v[32:33], off offset:2048 nt
	global_load_dwordx2 v[70:71], v[32:33], off offset:2560 nt
	global_load_dwordx2 v[74:75], v[32:33], off offset:3072 nt
	s_nop 0
	global_load_dwordx2 v[32:33], v[32:33], off offset:3584 nt
	s_waitcnt vmcnt(0)
	v_lshlrev_b32_e32 v48, 16, v34
	v_and_b32_e32 v49, 0xffff0000, v34
	v_lshlrev_b32_e32 v50, 16, v35
	v_and_b32_e32 v51, 0xffff0000, v35
	v_lshlrev_b32_e32 v52, 16, v36
	v_and_b32_e32 v53, 0xffff0000, v36
	v_lshlrev_b32_e32 v54, 16, v37
	v_and_b32_e32 v55, 0xffff0000, v37
	v_lshlrev_b32_e32 v56, 16, v38
	v_and_b32_e32 v57, 0xffff0000, v38
	v_lshlrev_b32_e32 v58, 16, v39
	v_and_b32_e32 v59, 0xffff0000, v39
	v_lshlrev_b32_e32 v60, 16, v40
	v_and_b32_e32 v61, 0xffff0000, v40
	v_lshlrev_b32_e32 v62, 16, v41
	v_and_b32_e32 v63, 0xffff0000, v41
	v_lshlrev_b32_e32 v64, 16, v42
	v_and_b32_e32 v65, 0xffff0000, v42
	v_lshlrev_b32_e32 v66, 16, v43
	v_and_b32_e32 v67, 0xffff0000, v43
	v_lshlrev_b32_e32 v68, 16, v70
	v_and_b32_e32 v69, 0xffff0000, v70
	v_lshlrev_b32_e32 v70, 16, v71
	v_and_b32_e32 v71, 0xffff0000, v71
	v_lshlrev_b32_e32 v72, 16, v74
	v_and_b32_e32 v73, 0xffff0000, v74
	v_lshlrev_b32_e32 v74, 16, v75
	v_and_b32_e32 v75, 0xffff0000, v75
	v_lshlrev_b32_e32 v76, 16, v32
	v_and_b32_e32 v77, 0xffff0000, v32
	v_lshlrev_b32_e32 v78, 16, v33
	v_and_b32_e32 v79, 0xffff0000, v33
	s_branch .LBB0_269

.LBB0_296:
	v_ashrrev_i32_e32 v85, 31, v84
	v_readlane_b32 s2, v252, 26
	v_mov_b32_e32 v88, v92
	v_lshlrev_b64 v[90:91], 12, v[84:85]
	v_readlane_b32 s3, v252, 27
	v_cmp_gt_i32_e64 s[36:37], s33, v84
	v_ashrrev_i32_e32 v89, 31, v88
	v_lshl_add_u64 v[0:1], s[2:3], 0, v[90:91]
	v_lshl_add_u64 v[86:87], v[88:89], 1, v[0:1]
	global_load_dwordx2 v[46:47], v[86:87], off nt
	global_load_dwordx2 v[44:45], v[86:87], off offset:512 nt
	global_load_dwordx2 v[42:43], v[86:87], off offset:1024 nt
	global_load_dwordx2 v[40:41], v[86:87], off offset:1536 nt
	global_load_dwordx2 v[6:7], v[86:87], off offset:2048 nt
	global_load_dwordx2 v[4:5], v[86:87], off offset:2560 nt
	global_load_dwordx2 v[2:3], v[86:87], off offset:3072 nt
	global_load_dwordx2 v[0:1], v[86:87], off offset:3584 nt
	s_movk_i32 s2, 0x1fff
	v_cmp_lt_i32_e32 vcc, s2, v84
	v_add_u32_e32 v192, 0xffffe000, v84
	s_and_saveexec_b64 s[2:3], vcc
	s_xor_b64 s[34:35], exec, s[2:3]
	s_cbranch_execz .LBB0_299
	v_readlane_b32 s2, v252, 9
	v_lshlrev_b64 v[8:9], 12, v[192:193]
	v_readlane_b32 s3, v252, 10
	v_mov_b32_e32 v36, 0
	s_mov_b64 s[38:39], -1
	v_lshl_add_u64 v[8:9], s[2:3], 0, v[8:9]
	v_lshl_add_u64 v[48:49], v[88:89], 1, v[8:9]
	s_mov_b64 s[2:3], 0
	v_mov_b32_e32 v37, v36
	v_mov_b32_e32 v38, v36
	v_mov_b32_e32 v39, v36
	v_mov_b32_e32 v32, v36
	v_mov_b32_e32 v33, v36
	v_mov_b32_e32 v34, v36
	v_mov_b32_e32 v35, v36
	v_mov_b32_e32 v8, v36
	v_mov_b32_e32 v9, v36
	v_mov_b32_e32 v10, v36
	v_mov_b32_e32 v11, v36
	v_mov_b32_e32 v12, v36
	v_mov_b32_e32 v13, v36
	v_mov_b32_e32 v14, v36
	v_mov_b32_e32 v15, v36
	v_mov_b32_e32 v16, v36
	v_mov_b32_e32 v17, v36
	v_mov_b32_e32 v18, v36
	v_mov_b32_e32 v19, v36
	v_mov_b32_e32 v20, v36
	v_mov_b32_e32 v21, v36
	v_mov_b32_e32 v22, v36
	v_mov_b32_e32 v23, v36
	v_mov_b32_e32 v24, v36
	v_mov_b32_e32 v25, v36
	v_mov_b32_e32 v26, v36
	v_mov_b32_e32 v27, v36
	v_mov_b32_e32 v28, v36
	v_mov_b32_e32 v29, v36
	v_mov_b32_e32 v30, v36
	v_mov_b32_e32 v31, v36
.LBB0_298:
	v_lshl_add_u64 v[50:51], s[2:3], 1, v[48:49]
	global_load_dwordx2 v[52:53], v[50:51], off nt
	global_load_dwordx2 v[54:55], v[50:51], off offset:512 nt
	global_load_dwordx2 v[56:57], v[50:51], off offset:1024 nt
	global_load_dwordx2 v[58:59], v[50:51], off offset:1536 nt
	global_load_dwordx2 v[60:61], v[50:51], off offset:2048 nt
	global_load_dwordx2 v[62:63], v[50:51], off offset:2560 nt
	global_load_dwordx2 v[64:65], v[50:51], off offset:3072 nt
	global_load_dwordx2 v[66:67], v[50:51], off offset:3584 nt
	v_add_co_u32_e32 v68, vcc, s42, v50
	s_mov_b64 s[2:3], 0x800000
	s_nop 0
	v_addc_co_u32_e32 v69, vcc, 0, v51, vcc
	global_load_dwordx2 v[70:71], v[68:69], off nt
	global_load_dwordx2 v[72:73], v[68:69], off offset:512 nt
	global_load_dwordx2 v[74:75], v[68:69], off offset:1024 nt
	global_load_dwordx2 v[76:77], v[68:69], off offset:1536 nt
	global_load_dwordx2 v[78:79], v[68:69], off offset:2048 nt
	global_load_dwordx2 v[80:81], v[68:69], off offset:2560 nt
	global_load_dwordx2 v[82:83], v[68:69], off offset:3072 nt
	s_nop 0
	global_load_dwordx2 v[68:69], v[68:69], off offset:3584 nt
	v_add_co_u32_e32 v94, vcc, s96, v50
	s_waitcnt vmcnt(0)
	v_lshlrev_b32_e32 v124, 16, v52
	v_addc_co_u32_e32 v95, vcc, 0, v51, vcc
	global_load_dwordx2 v[96:97], v[94:95], off nt
	global_load_dwordx2 v[98:99], v[94:95], off offset:512 nt
	global_load_dwordx2 v[100:101], v[94:95], off offset:1024 nt
	global_load_dwordx2 v[102:103], v[94:95], off offset:1536 nt
	global_load_dwordx2 v[104:105], v[94:95], off offset:2048 nt
	global_load_dwordx2 v[106:107], v[94:95], off offset:2560 nt
	global_load_dwordx2 v[108:109], v[94:95], off offset:3072 nt
	s_nop 0
	global_load_dwordx2 v[94:95], v[94:95], off offset:3584 nt
	v_add_co_u32_e32 v50, vcc, s43, v50
	v_and_b32_e32 v125, 0xffff0000, v52
	s_nop 0
	v_addc_co_u32_e32 v51, vcc, 0, v51, vcc
	global_load_dwordx2 v[110:111], v[50:51], off nt
	global_load_dwordx2 v[112:113], v[50:51], off offset:512 nt
	global_load_dwordx2 v[114:115], v[50:51], off offset:1024 nt
	global_load_dwordx2 v[116:117], v[50:51], off offset:1536 nt
	global_load_dwordx2 v[118:119], v[50:51], off offset:2048 nt
	global_load_dwordx2 v[120:121], v[50:51], off offset:2560 nt
	global_load_dwordx2 v[122:123], v[50:51], off offset:3072 nt
	s_nop 0
	global_load_dwordx2 v[50:51], v[50:51], off offset:3584 nt
	v_lshlrev_b32_e32 v52, 16, v53
	v_and_b32_e32 v53, 0xffff0000, v53
	v_pk_add_f32 v[38:39], v[38:39], v[52:53]
	v_lshlrev_b32_e32 v52, 16, v54
	v_and_b32_e32 v53, 0xffff0000, v54
	v_lshlrev_b32_e32 v54, 16, v55
	v_and_b32_e32 v55, 0xffff0000, v55
	v_pk_add_f32 v[32:33], v[32:33], v[52:53]
	v_lshlrev_b32_e32 v52, 16, v56
	v_and_b32_e32 v53, 0xffff0000, v56
	v_pk_add_f32 v[34:35], v[34:35], v[54:55]
	v_lshlrev_b32_e32 v54, 16, v57
	v_and_b32_e32 v55, 0xffff0000, v57
	v_pk_add_f32 v[8:9], v[8:9], v[52:53]
	v_lshlrev_b32_e32 v52, 16, v58
	v_and_b32_e32 v53, 0xffff0000, v58
	v_pk_add_f32 v[10:11], v[10:11], v[54:55]
	v_lshlrev_b32_e32 v54, 16, v59
	v_and_b32_e32 v55, 0xffff0000, v59
	v_pk_add_f32 v[12:13], v[12:13], v[52:53]
	v_lshlrev_b32_e32 v52, 16, v60
	v_and_b32_e32 v53, 0xffff0000, v60
	v_pk_add_f32 v[14:15], v[14:15], v[54:55]
	v_lshlrev_b32_e32 v54, 16, v61
	v_and_b32_e32 v55, 0xffff0000, v61
	v_pk_add_f32 v[16:17], v[16:17], v[52:53]
	v_lshlrev_b32_e32 v52, 16, v62
	v_and_b32_e32 v53, 0xffff0000, v62
	v_pk_add_f32 v[18:19], v[18:19], v[54:55]
	v_lshlrev_b32_e32 v54, 16, v63
	v_and_b32_e32 v55, 0xffff0000, v63
	v_pk_add_f32 v[20:21], v[20:21], v[52:53]
	v_lshlrev_b32_e32 v52, 16, v64
	v_and_b32_e32 v53, 0xffff0000, v64
	v_pk_add_f32 v[22:23], v[22:23], v[54:55]
	v_lshlrev_b32_e32 v54, 16, v65
	v_and_b32_e32 v55, 0xffff0000, v65
	v_pk_add_f32 v[24:25], v[24:25], v[52:53]
	v_lshlrev_b32_e32 v52, 16, v66
	v_and_b32_e32 v53, 0xffff0000, v66
	v_pk_add_f32 v[36:37], v[36:37], v[124:125]
	v_pk_add_f32 v[26:27], v[26:27], v[54:55]
	v_lshlrev_b32_e32 v54, 16, v67
	v_and_b32_e32 v55, 0xffff0000, v67
	v_pk_add_f32 v[28:29], v[28:29], v[52:53]
	v_lshlrev_b32_e32 v52, 16, v70
	v_and_b32_e32 v53, 0xffff0000, v70
	v_pk_add_f32 v[30:31], v[30:31], v[54:55]
	v_lshlrev_b32_e32 v54, 16, v71
	v_and_b32_e32 v55, 0xffff0000, v71
	v_pk_add_f32 v[36:37], v[36:37], v[52:53]
	v_lshlrev_b32_e32 v52, 16, v72
	v_and_b32_e32 v53, 0xffff0000, v72
	v_pk_add_f32 v[38:39], v[38:39], v[54:55]
	v_lshlrev_b32_e32 v54, 16, v73
	v_and_b32_e32 v55, 0xffff0000, v73
	v_pk_add_f32 v[32:33], v[32:33], v[52:53]
	v_lshlrev_b32_e32 v52, 16, v74
	v_and_b32_e32 v53, 0xffff0000, v74
	v_pk_add_f32 v[34:35], v[34:35], v[54:55]
	v_lshlrev_b32_e32 v54, 16, v75
	v_and_b32_e32 v55, 0xffff0000, v75
	v_pk_add_f32 v[8:9], v[8:9], v[52:53]
	v_lshlrev_b32_e32 v52, 16, v76
	v_and_b32_e32 v53, 0xffff0000, v76
	v_pk_add_f32 v[10:11], v[10:11], v[54:55]
	v_lshlrev_b32_e32 v54, 16, v77
	v_and_b32_e32 v55, 0xffff0000, v77
	v_pk_add_f32 v[12:13], v[12:13], v[52:53]
	v_lshlrev_b32_e32 v52, 16, v78
	v_and_b32_e32 v53, 0xffff0000, v78
	v_pk_add_f32 v[14:15], v[14:15], v[54:55]
	v_lshlrev_b32_e32 v54, 16, v79
	v_and_b32_e32 v55, 0xffff0000, v79
	v_pk_add_f32 v[16:17], v[16:17], v[52:53]
	v_lshlrev_b32_e32 v52, 16, v80
	v_and_b32_e32 v53, 0xffff0000, v80
	v_pk_add_f32 v[18:19], v[18:19], v[54:55]
	v_lshlrev_b32_e32 v54, 16, v81
	v_and_b32_e32 v55, 0xffff0000, v81
	v_pk_add_f32 v[20:21], v[20:21], v[52:53]
	v_lshlrev_b32_e32 v52, 16, v82
	v_and_b32_e32 v53, 0xffff0000, v82
	v_pk_add_f32 v[22:23], v[22:23], v[54:55]
	v_lshlrev_b32_e32 v54, 16, v83
	v_and_b32_e32 v55, 0xffff0000, v83
	v_pk_add_f32 v[24:25], v[24:25], v[52:53]
	v_lshlrev_b32_e32 v52, 16, v68
	v_and_b32_e32 v53, 0xffff0000, v68
	v_pk_add_f32 v[26:27], v[26:27], v[54:55]
	v_lshlrev_b32_e32 v54, 16, v69
	v_and_b32_e32 v55, 0xffff0000, v69
	v_pk_add_f32 v[28:29], v[28:29], v[52:53]
	s_waitcnt vmcnt(0)
	v_lshlrev_b32_e32 v52, 16, v96
	v_and_b32_e32 v53, 0xffff0000, v96
	v_pk_add_f32 v[30:31], v[30:31], v[54:55]
	v_lshlrev_b32_e32 v54, 16, v97
	v_and_b32_e32 v55, 0xffff0000, v97
	v_pk_add_f32 v[36:37], v[36:37], v[52:53]
	v_lshlrev_b32_e32 v52, 16, v98
	v_and_b32_e32 v53, 0xffff0000, v98
	v_pk_add_f32 v[38:39], v[38:39], v[54:55]
	v_lshlrev_b32_e32 v54, 16, v99
	v_and_b32_e32 v55, 0xffff0000, v99
	v_pk_add_f32 v[32:33], v[32:33], v[52:53]
	v_lshlrev_b32_e32 v52, 16, v100
	v_and_b32_e32 v53, 0xffff0000, v100
	v_pk_add_f32 v[34:35], v[34:35], v[54:55]
	v_lshlrev_b32_e32 v54, 16, v101
	v_and_b32_e32 v55, 0xffff0000, v101
	v_pk_add_f32 v[8:9], v[8:9], v[52:53]
	v_lshlrev_b32_e32 v52, 16, v102
	v_and_b32_e32 v53, 0xffff0000, v102
	v_pk_add_f32 v[10:11], v[10:11], v[54:55]
	v_lshlrev_b32_e32 v54, 16, v103
	v_and_b32_e32 v55, 0xffff0000, v103
	v_pk_add_f32 v[12:13], v[12:13], v[52:53]
	v_lshlrev_b32_e32 v52, 16, v104
	v_and_b32_e32 v53, 0xffff0000, v104
	v_pk_add_f32 v[14:15], v[14:15], v[54:55]
	v_lshlrev_b32_e32 v54, 16, v105
	v_and_b32_e32 v55, 0xffff0000, v105
	v_pk_add_f32 v[16:17], v[16:17], v[52:53]
	v_lshlrev_b32_e32 v52, 16, v106
	v_and_b32_e32 v53, 0xffff0000, v106
	v_pk_add_f32 v[18:19], v[18:19], v[54:55]
	v_lshlrev_b32_e32 v54, 16, v107
	v_and_b32_e32 v55, 0xffff0000, v107
	v_pk_add_f32 v[20:21], v[20:21], v[52:53]
	v_lshlrev_b32_e32 v52, 16, v108
	v_and_b32_e32 v53, 0xffff0000, v108
	v_pk_add_f32 v[22:23], v[22:23], v[54:55]
	v_lshlrev_b32_e32 v54, 16, v109
	v_and_b32_e32 v55, 0xffff0000, v109
	v_pk_add_f32 v[24:25], v[24:25], v[52:53]
	v_lshlrev_b32_e32 v52, 16, v94
	v_and_b32_e32 v53, 0xffff0000, v94
	v_pk_add_f32 v[26:27], v[26:27], v[54:55]
	v_lshlrev_b32_e32 v54, 16, v95
	v_and_b32_e32 v55, 0xffff0000, v95
	v_pk_add_f32 v[28:29], v[28:29], v[52:53]
	v_lshlrev_b32_e32 v52, 16, v110
	v_and_b32_e32 v53, 0xffff0000, v110
	v_pk_add_f32 v[30:31], v[30:31], v[54:55]
	v_lshlrev_b32_e32 v54, 16, v111
	v_and_b32_e32 v55, 0xffff0000, v111
	v_pk_add_f32 v[36:37], v[36:37], v[52:53]
	v_lshlrev_b32_e32 v52, 16, v112
	v_and_b32_e32 v53, 0xffff0000, v112
	v_pk_add_f32 v[38:39], v[38:39], v[54:55]
	v_lshlrev_b32_e32 v54, 16, v113
	v_and_b32_e32 v55, 0xffff0000, v113
	v_pk_add_f32 v[32:33], v[32:33], v[52:53]
	v_lshlrev_b32_e32 v52, 16, v114
	v_and_b32_e32 v53, 0xffff0000, v114
	v_pk_add_f32 v[34:35], v[34:35], v[54:55]
	v_lshlrev_b32_e32 v54, 16, v115
	v_and_b32_e32 v55, 0xffff0000, v115
	v_pk_add_f32 v[8:9], v[8:9], v[52:53]
	v_lshlrev_b32_e32 v52, 16, v116
	v_and_b32_e32 v53, 0xffff0000, v116
	v_pk_add_f32 v[10:11], v[10:11], v[54:55]
	v_lshlrev_b32_e32 v54, 16, v117
	v_and_b32_e32 v55, 0xffff0000, v117
	v_pk_add_f32 v[12:13], v[12:13], v[52:53]
	v_lshlrev_b32_e32 v52, 16, v118
	v_and_b32_e32 v53, 0xffff0000, v118
	v_pk_add_f32 v[14:15], v[14:15], v[54:55]
	v_lshlrev_b32_e32 v54, 16, v119
	v_and_b32_e32 v55, 0xffff0000, v119
	v_pk_add_f32 v[16:17], v[16:17], v[52:53]
	v_lshlrev_b32_e32 v52, 16, v120
	v_and_b32_e32 v53, 0xffff0000, v120
	v_pk_add_f32 v[18:19], v[18:19], v[54:55]
	v_lshlrev_b32_e32 v54, 16, v121
	v_and_b32_e32 v55, 0xffff0000, v121
	v_pk_add_f32 v[20:21], v[20:21], v[52:53]
	v_lshlrev_b32_e32 v52, 16, v122
	v_and_b32_e32 v53, 0xffff0000, v122
	v_pk_add_f32 v[22:23], v[22:23], v[54:55]
	v_lshlrev_b32_e32 v54, 16, v123
	v_and_b32_e32 v55, 0xffff0000, v123
	v_pk_add_f32 v[24:25], v[24:25], v[52:53]
	v_lshlrev_b32_e32 v52, 16, v50
	v_and_b32_e32 v53, 0xffff0000, v50
	v_lshlrev_b32_e32 v50, 16, v51
	v_and_b32_e32 v51, 0xffff0000, v51
	v_pk_add_f32 v[26:27], v[26:27], v[54:55]
	v_pk_add_f32 v[30:31], v[30:31], v[50:51]
	v_pk_add_f32 v[28:29], v[28:29], v[52:53]
	s_and_b64 vcc, exec, s[38:39]
	s_mov_b64 s[38:39], 0
	s_cbranch_vccnz .LBB0_298
.LBB0_299:
	s_andn2_saveexec_b64 s[2:3], s[34:35]
	s_cbranch_execz .LBB0_301
	v_readlane_b32 s4, v252, 7
	v_readlane_b32 s5, v252, 8
	s_nop 1
	v_lshl_add_u64 v[8:9], s[4:5], 0, v[90:91]
	v_lshl_add_u64 v[8:9], v[88:89], 1, v[8:9]
	global_load_dwordx2 v[10:11], v[8:9], off nt
	global_load_dwordx2 v[12:13], v[8:9], off offset:512 nt
	global_load_dwordx2 v[14:15], v[8:9], off offset:1024 nt
	global_load_dwordx2 v[16:17], v[8:9], off offset:1536 nt
	global_load_dwordx2 v[18:19], v[8:9], off offset:2048 nt
	global_load_dwordx2 v[22:23], v[8:9], off offset:2560 nt
	global_load_dwordx2 v[26:27], v[8:9], off offset:3072 nt
	global_load_dwordx2 v[30:31], v[8:9], off offset:3584 nt
	s_waitcnt vmcnt(0)
	v_lshlrev_b32_e32 v36, 16, v10
	v_and_b32_e32 v37, 0xffff0000, v10
	v_lshlrev_b32_e32 v38, 16, v11
	v_and_b32_e32 v39, 0xffff0000, v11
	v_lshlrev_b32_e32 v32, 16, v12
	v_and_b32_e32 v33, 0xffff0000, v12
	v_lshlrev_b32_e32 v34, 16, v13
	v_and_b32_e32 v35, 0xffff0000, v13
	v_lshlrev_b32_e32 v8, 16, v14
	v_and_b32_e32 v9, 0xffff0000, v14
	v_lshlrev_b32_e32 v10, 16, v15
	v_and_b32_e32 v11, 0xffff0000, v15
	v_lshlrev_b32_e32 v12, 16, v16
	v_and_b32_e32 v13, 0xffff0000, v16
	v_lshlrev_b32_e32 v14, 16, v17
	v_and_b32_e32 v15, 0xffff0000, v17
	v_lshlrev_b32_e32 v16, 16, v18
	v_and_b32_e32 v17, 0xffff0000, v18
	v_lshlrev_b32_e32 v18, 16, v19
	v_and_b32_e32 v19, 0xffff0000, v19
	v_lshlrev_b32_e32 v20, 16, v22
	v_and_b32_e32 v21, 0xffff0000, v22
	v_lshlrev_b32_e32 v22, 16, v23
	v_and_b32_e32 v23, 0xffff0000, v23
	v_lshlrev_b32_e32 v24, 16, v26
	v_and_b32_e32 v25, 0xffff0000, v26
	v_lshlrev_b32_e32 v26, 16, v27
	v_and_b32_e32 v27, 0xffff0000, v27
	v_lshlrev_b32_e32 v28, 16, v30
	v_and_b32_e32 v29, 0xffff0000, v30
	v_lshlrev_b32_e32 v30, 16, v31
	v_and_b32_e32 v31, 0xffff0000, v31
